# attention: K and bias-table loads issued before waiting on the Q rows (vmcnt(40) instead of vmcnt(0))
# baseline (speedup 1.0000x reference)
; __device__ __forceinline__ void attn_phase(LAS unsigned char* lds, const bf16_t* QKV, const float* TBL  , bf16_t* O, int tid, int wave, int lane, int G) {
;     ...
;         {
;             const bf16_t* qsrc = qh + (size_t)(r * 64 + 16 * qt + (lane >> 3)) * 64 + (lane & 7) * 8;
;             const u32x4 q0 = *(const u32x4*)qsrc, q1 = *(const u32x4*)(qsrc + (size_t)8 * 64);
;             *(LAS u32x4*)(vt + (lane >> 3) * 144 + (lane & 7) * 16) = q0; *(LAS u32x4*)(vt + ((lane >> 3) + 8) * 144 + (lane & 7) * 16) = q1;
;             qf[0] = *(const LAS bf16x8*)(vt + fr * 144 + 16 * fq); qf[1] = *(const LAS bf16x8*)(vt + fr * 144 + 64 + 16 * fq);
;             asm volatile("s_waitcnt lgkmcnt(0)" ::: "memory"); }
;         const int vkey = lane >> 3, vch = lane & 7;
;         const bf16_t* vsrc = vh + (size_t)(r0 * 64 + kc0 + vkey) * 64 + vch * 8;
;         u32x4 vr[4][2][4];
;         f32x4 s[8][2]; u32x4 kr[4][2][4];
;         const bf16_t* ksrc = kh + (size_t)(r0 * 64 + kc0 + vkey) * 64 + vch * 8;
; #pragma unroll
;         for (int i = 0; i < 8; ++i) { const bf16_t* src = ksrc + (size_t)i * 64 * 64;
; #pragma unroll
;             for (int j = 0; j < 4; ++j) kr[i >> 1][i & 1][j] = *(const u32x4*)(src + (size_t)j * 8 * 64); }
; #pragma unroll
;         for (int i = 0; i < 8; ++i)
; #pragma unroll
;             for (int t = 0; t < 2; ++t) s[i][t] = i < 4 ? *(const f32x4*)(tb + (i * 2 + t) * 256) : (f32x4){0.f, 0.f, 0.f, 0.f};
.LBB0_366:
	s_bfe_u32 s10, s12, 0x70006
	v_sub_u32_e64 v0, s10, 4 clamp
	s_bfe_u32 s17, s12, 0x40002
	v_readfirstlane_b32 s9, v0
	s_min_u32 s20, s9, 0x78
	s_lshl_b32 s18, s10, 6
	s_sub_i32 s10, s10, s20
	s_ashr_i32 s8, s12, 13
	s_lshl_b32 s10, s10, 6
	s_lshl_b32 s11, s17, 2
	s_or_b32 s10, s10, s11
	s_lshl_b32 s21, s8, 4
	s_or_b32 s10, s10, s15
	s_or_b32 s30, s21, s17
	s_ashr_i32 s11, s10, 31
	s_ashr_i32 s31, s30, 31
	s_ashr_i32 s9, s8, 31
	s_lshl_b64 s[10:11], s[10:11], 14
	s_lshl_b64 s[30:31], s[30:31], 20
	s_add_u32 s30, s13, s30
	v_or_b32_e32 v0, s18, v164
	s_addc_u32 s31, s14, s31
	v_lshlrev_b32_e32 v0, 7, v0
	v_lshl_add_u64 v[2:3], s[30:31], 0, v[0:1]
	v_mov_b32_e32 v167, v1
	v_lshl_add_u64 v[6:7], v[2:3], 0, v[166:167]
	global_load_dwordx4 v[2:5], v[6:7], off
	s_nop 0
	global_load_dwordx4 v[6:9], v[6:7], off offset:1024
	s_lshl_b32 s20, s20, 6
	s_or_b32 s19, s19, s20
	v_or_b32_e32 v0, s19, v165
	v_lshlrev_b32_e32 v0, 7, v0
	v_lshl_add_u64 v[10:11], s[30:31], 0, v[0:1]
	v_lshl_add_u64 v[18:19], v[10:11], 0, v[166:167]
	s_brev_b32 s19, 16
	v_add_co_u32_e32 v20, vcc, s19, v18
	s_mov_b32 s19, 0x8002000
	s_nop 0
	v_addc_co_u32_e32 v21, vcc, 0, v19, vcc
	v_add_co_u32_e32 v40, vcc, s19, v18
	s_mov_b32 s19, 0x8004000
	s_nop 0
	v_addc_co_u32_e32 v41, vcc, 0, v19, vcc
	v_add_co_u32_e32 v56, vcc, s19, v18
	s_mov_b32 s19, 0x8006000
	s_nop 0
	v_addc_co_u32_e32 v57, vcc, 0, v19, vcc
	v_add_co_u32_e32 v72, vcc, s19, v18
	s_mov_b32 s19, 0x8008000
	s_nop 0
	v_addc_co_u32_e32 v73, vcc, 0, v19, vcc
	v_add_co_u32_e32 v88, vcc, s19, v18
	s_mov_b32 s19, 0x800a000
	s_nop 0
	v_addc_co_u32_e32 v89, vcc, 0, v19, vcc
	v_add_co_u32_e32 v104, vcc, s19, v18
	s_mov_b32 s19, 0x800c000
	s_nop 0
	v_addc_co_u32_e32 v105, vcc, 0, v19, vcc
	v_add_u32_e32 v0, v200, v201
	s_mov_b64 s[30:31], 0x8000000
	v_add_co_u32_e32 v120, vcc, s19, v18
	v_lshl_add_u64 v[24:25], v[18:19], 0, s[30:31]
	s_nop 0
	v_addc_co_u32_e32 v121, vcc, 0, v19, vcc
	s_mov_b32 s19, 0x800e000
	v_add_co_u32_e32 v128, vcc, s19, v18
	v_lshl_add_u64 v[192:193], v[162:163], 0, s[10:11]
	s_nop 0
	v_addc_co_u32_e32 v129, vcc, 0, v19, vcc
	s_movk_i32 s10, 0x1000
	v_add_co_u32_e32 v140, vcc, s10, v192
	s_movk_i32 s10, 0x2000
	s_nop 0
	v_addc_co_u32_e32 v141, vcc, 0, v193, vcc
	v_add_co_u32_e32 v194, vcc, s10, v192
	s_lshl_b64 s[8:9], s[8:9], 13
	s_nop 0
	v_addc_co_u32_e32 v195, vcc, 0, v193, vcc
	s_or_b32 s8, s8, s18
	global_load_dwordx4 v[10:13], v[24:25], off offset:1024
	global_load_dwordx4 v[14:17], v[24:25], off offset:2048
	s_nop 0
	global_load_dwordx4 v[20:23], v[20:21], off
	s_nop 0
	global_load_dwordx4 v[24:27], v[24:25], off offset:3072
	s_nop 0
	global_load_dwordx4 v[28:31], v[40:41], off
	global_load_dwordx4 v[32:35], v[40:41], off offset:1024
	global_load_dwordx4 v[36:39], v[40:41], off offset:2048
	s_nop 0
	global_load_dwordx4 v[40:43], v[40:41], off offset:3072
	s_nop 0
	global_load_dwordx4 v[44:47], v[56:57], off
	global_load_dwordx4 v[48:51], v[56:57], off offset:1024
	global_load_dwordx4 v[52:55], v[56:57], off offset:2048
	s_nop 0
	global_load_dwordx4 v[56:59], v[56:57], off offset:3072
	s_nop 0
	global_load_dwordx4 v[60:63], v[72:73], off
	global_load_dwordx4 v[64:67], v[72:73], off offset:1024
	global_load_dwordx4 v[68:71], v[72:73], off offset:2048
	s_nop 0
	global_load_dwordx4 v[72:75], v[72:73], off offset:3072
	s_nop 0
	global_load_dwordx4 v[76:79], v[88:89], off
	global_load_dwordx4 v[80:83], v[88:89], off offset:1024
	global_load_dwordx4 v[84:87], v[88:89], off offset:2048
	s_nop 0
	global_load_dwordx4 v[88:91], v[88:89], off offset:3072
	s_nop 0
	global_load_dwordx4 v[92:95], v[104:105], off
	global_load_dwordx4 v[96:99], v[104:105], off offset:1024
	global_load_dwordx4 v[100:103], v[104:105], off offset:2048
	s_nop 0
	global_load_dwordx4 v[104:107], v[104:105], off offset:3072
	s_nop 0
	global_load_dwordx4 v[108:111], v[120:121], off
	global_load_dwordx4 v[112:115], v[120:121], off offset:1024
	global_load_dwordx4 v[116:119], v[120:121], off offset:2048
	s_nop 0
	global_load_dwordx4 v[120:123], v[120:121], off offset:3072
	s_nop 0
	global_load_dwordx4 v[124:127], v[128:129], off
	global_load_dwordx4 v[158:161], v[128:129], off offset:1024
	global_load_dwordx4 v[168:171], v[128:129], off offset:2048
	global_load_dwordx4 v[172:175], v[128:129], off offset:3072
	s_nop 0
	global_load_dwordx4 v[128:131], v[192:193], off
	global_load_dwordx4 v[132:135], v[192:193], off offset:1024
	global_load_dwordx4 v[136:139], v[192:193], off offset:2048
	global_load_dwordx4 v[146:149], v[192:193], off offset:3072
	global_load_dwordx4 v[176:179], v[140:141], off offset:1024
	global_load_dwordx4 v[180:183], v[140:141], off offset:2048
	global_load_dwordx4 v[184:187], v[194:195], off offset:-4096
	global_load_dwordx4 v[188:191], v[140:141], off offset:3072
	s_waitcnt vmcnt(40)
	ds_write_b128 v209, v[2:5]
	ds_write_b128 v209, v[6:9] offset:1152
	ds_read_b128 v[6:9], v0
	ds_read_b128 v[2:5], v0 offset:64
	s_waitcnt lgkmcnt(0)
	s_waitcnt vmcnt(37)
	ds_write_b128 v209, v[20:23]
	ds_write_b128 v209, v[10:13] offset:1152
	ds_write_b128 v209, v[14:17] offset:2304
	s_waitcnt vmcnt(36)
	ds_write_b128 v209, v[24:27] offset:3456
	s_waitcnt vmcnt(35)
	ds_write_b128 v209, v[28:31] offset:4608
	s_waitcnt vmcnt(34)
	ds_write_b128 v209, v[32:35] offset:5760
	s_waitcnt vmcnt(33)
	ds_write_b128 v209, v[36:39] offset:6912
	s_waitcnt vmcnt(32)
	ds_write_b128 v209, v[40:43] offset:8064
	ds_read_b128 v[10:13], v210
	ds_read_b128 v[14:17], v210 offset:64
	ds_read_b128 v[20:23], v210 offset:2304
	ds_read_b128 v[24:27], v210 offset:2368
	s_movk_i32 s10, 0x3000
	s_waitcnt vmcnt(7) lgkmcnt(3)
; __device__ __forceinline__ void attn_phase(LAS unsigned char* lds, const bf16_t* QKV, const float* TBL  , bf16_t* O, int tid, int wave, int lane, int G) {
;     ...
;         for (int ip = 0; ip < 4; ++ip) {
; #pragma unroll
;             for (int rr = 0; rr < 2; ++rr) { LAS unsigned char* dst = vt + rr * 4608 + vkey * 144 + vch * 16;
; #pragma unroll
;                 for (int j = 0; j < 4; ++j) *(LAS u32x4*)(dst + j * 8 * 144) = kr[ip][rr][j]; }
;             if (ip == 1) {
; #pragma unroll
;                 for (int i = 0; i < 4; ++i)
; #pragma unroll
;                     for (int t = 0; t < 2; ++t) tb2[i][t] = *(const f32x4*)(tb + ((i + 4) * 2 + t) * 256); }
; #pragma unroll
;             for (int rr = 0; rr < 2; ++rr)
; #pragma unroll
;                 for (int t = 0; t < 2; ++t) { const LAS unsigned char* kp = vt + rr * 4608 + (16 * t + fr) * 144 + 16 * fq;
;                     const bf16x8 k0 = *(const LAS bf16x8*)kp, k1 = *(const LAS bf16x8*)(kp + 64);
;                     s[2 * ip + rr][t] = __builtin_amdgcn_mfma_f32_16x16x32_bf16(k0, qf[0], s[2 * ip + rr][t], 0, 0, 0); s[2 * ip + rr][t] = __builtin_amdgcn_mfma_f32_16x16x32_bf16(k1, qf[1], s[2 * ip + rr][t], 0, 0, 0); }
;             asm volatile("s_waitcnt lgkmcnt(0)" ::: "memory");
;         }
; #pragma unroll
;         for (int i = 0; i < 4; ++i)
; #pragma unroll
;             for (int t = 0; t < 2; ++t) s[i + 4][t] = s[i + 4][t] + tb2[i][t];
	v_mfma_f32_16x16x32_bf16 v[10:13], v[10:13], v[6:9], v[128:131]
	s_waitcnt lgkmcnt(2)
	v_mfma_f32_16x16x32_bf16 v[154:157], v[14:17], v[2:5], v[10:13]
	ds_read_b128 v[14:17], v210 offset:4672
	s_nop 4
	ds_read_b128 v[10:13], v210 offset:4608
	s_waitcnt vmcnt(6) lgkmcnt(3)
	v_mfma_f32_16x16x32_bf16 v[20:23], v[20:23], v[6:9], v[132:135]
	s_waitcnt lgkmcnt(2)
	v_mfma_f32_16x16x32_bf16 v[150:153], v[24:27], v[2:5], v[20:23]
	s_nop 5
	ds_read_b128 v[20:23], v210 offset:6912
	ds_read_b128 v[24:27], v210 offset:6976
	s_waitcnt lgkmcnt(0)
	ds_write_b128 v209, v[44:47]
	ds_write_b128 v209, v[48:51] offset:1152
	ds_write_b128 v209, v[52:55] offset:2304
	s_waitcnt vmcnt(5) lgkmcnt(5)
	v_mfma_f32_16x16x32_bf16 v[10:13], v[10:13], v[6:9], v[136:139]
	ds_write_b128 v209, v[56:59] offset:3456
	ds_write_b128 v209, v[60:63] offset:4608
	ds_write_b128 v209, v[64:67] offset:5760
	ds_write_b128 v209, v[68:71] offset:6912
	ds_write_b128 v209, v[72:75] offset:8064
	v_add_co_u32_e32 v48, vcc, s10, v192
	v_mfma_f32_16x16x32_bf16 v[142:145], v[14:17], v[2:5], v[10:13]
	ds_read_b128 v[14:17], v210
	v_addc_co_u32_e32 v49, vcc, 0, v193, vcc
	s_waitcnt vmcnt(4) lgkmcnt(10)
	v_mfma_f32_16x16x32_bf16 v[10:13], v[20:23], v[6:9], v[146:149]
	s_mov_b64 s[10:11], 0x10000000
	s_waitcnt lgkmcnt(9)
	v_mfma_f32_16x16x32_bf16 v[146:149], v[24:27], v[2:5], v[10:13]
	s_nop 4
	ds_read_b128 v[10:13], v210 offset:64
	s_waitcnt vmcnt(1) lgkmcnt(1)
	v_mfma_f32_16x16x32_bf16 v[14:17], v[14:17], v[6:9], v[184:187]
	ds_read_b128 v[20:23], v210 offset:2304
	ds_read_b128 v[24:27], v210 offset:2368
	s_waitcnt lgkmcnt(2)
	v_mfma_f32_16x16x32_bf16 v[138:141], v[10:13], v[2:5], v[14:17]
	global_load_dwordx4 v[10:13], v[194:195], off
	s_nop 2
	global_load_dwordx4 v[14:17], v[194:195], off offset:1024
	ds_read_b128 v[28:31], v210 offset:4608
	global_load_dwordx4 v[32:35], v[194:195], off offset:2048
	global_load_dwordx4 v[36:39], v[194:195], off offset:3072
	s_waitcnt lgkmcnt(2)
	v_mfma_f32_16x16x32_bf16 v[20:23], v[20:23], v[6:9], v[176:179]
	ds_read_b128 v[40:43], v210 offset:4672
	s_waitcnt lgkmcnt(2)
	v_mfma_f32_16x16x32_bf16 v[134:137], v[24:27], v[2:5], v[20:23]
	s_waitcnt lgkmcnt(1)
	v_mfma_f32_16x16x32_bf16 v[20:23], v[28:31], v[6:9], v[180:183]
	global_load_dwordx4 v[24:27], v[48:49], off
	global_load_dwordx4 v[28:31], v[48:49], off offset:1024
	global_load_dwordx4 v[44:47], v[48:49], off offset:2048
	s_nop 0
	global_load_dwordx4 v[48:51], v[48:49], off offset:3072
	s_waitcnt lgkmcnt(0)
	v_mfma_f32_16x16x32_bf16 v[130:133], v[40:43], v[2:5], v[20:23]
	s_nop 2
	ds_read_b128 v[20:23], v210 offset:6912
	ds_read_b128 v[40:43], v210 offset:6976
	s_waitcnt lgkmcnt(0)
	ds_write_b128 v209, v[76:79]
	ds_write_b128 v209, v[80:83] offset:1152
	ds_write_b128 v209, v[84:87] offset:2304
	ds_write_b128 v209, v[88:91] offset:3456
	ds_write_b128 v209, v[92:95] offset:4608
	ds_write_b128 v209, v[96:99] offset:5760
	ds_write_b128 v209, v[100:103] offset:6912
	ds_write_b128 v209, v[104:107] offset:8064
	ds_read_b128 v[52:55], v210
	ds_read_b128 v[56:59], v210 offset:64
	s_waitcnt lgkmcnt(1)
	v_mfma_f32_16x16x32_bf16 v[52:55], v[52:55], v[6:9], 0
	ds_read_b128 v[60:63], v210 offset:2304
	ds_read_b128 v[64:67], v210 offset:4608
	s_waitcnt lgkmcnt(2)
	v_mfma_f32_16x16x32_bf16 v[52:55], v[56:59], v[2:5], v[52:55]
	ds_read_b128 v[56:59], v210 offset:2368
	s_waitcnt lgkmcnt(2)
	v_mfma_f32_16x16x32_bf16 v[60:63], v[60:63], v[6:9], 0
	s_waitcnt vmcnt(7)
	s_nop 3
	v_pk_add_f32 v[196:197], v[12:13], v[54:55]
	s_waitcnt lgkmcnt(0)
	v_mfma_f32_16x16x32_bf16 v[56:59], v[56:59], v[2:5], v[60:63]
	v_add_f32_e64 v198, v10, v52
	v_add_f32_e64 v199, v11, v53
	s_nop 0
	ds_read_b128 v[60:63], v210 offset:4672
	v_mfma_f32_16x16x32_bf16 v[64:67], v[64:67], v[6:9], 0
	ds_read_b128 v[68:71], v210 offset:6912
	ds_read_b128 v[72:75], v210 offset:6976
	s_waitcnt lgkmcnt(0)
	ds_write_b128 v209, v[108:111]
	ds_write_b128 v209, v[112:115] offset:1152
	ds_write_b128 v209, v[116:119] offset:2304
	ds_write_b128 v209, v[120:123] offset:3456
	ds_write_b128 v209, v[124:127] offset:4608
	ds_write_b128 v209, v[158:161] offset:5760
	ds_write_b128 v209, v[168:171] offset:6912
	ds_write_b128 v209, v[172:175] offset:8064
	s_waitcnt lgkmcnt(10)
	v_mfma_f32_16x16x32_bf16 v[60:63], v[60:63], v[2:5], v[64:67]
	ds_read_b128 v[76:79], v210 offset:2304
	s_waitcnt vmcnt(6)
	v_pk_add_f32 v[192:193], v[16:17], v[58:59]
	v_pk_add_f32 v[194:195], v[14:15], v[56:57]
	s_waitcnt lgkmcnt(10)
	v_mfma_f32_16x16x32_bf16 v[64:67], v[68:71], v[6:9], 0
	ds_read_b128 v[68:71], v210
	s_waitcnt lgkmcnt(10)
	v_mfma_f32_16x16x32_bf16 v[64:67], v[72:75], v[2:5], v[64:67]
	ds_read_b128 v[72:75], v210 offset:64
	s_waitcnt lgkmcnt(1)
	v_mfma_f32_16x16x32_bf16 v[68:71], v[68:71], v[6:9], 0
	s_waitcnt vmcnt(4)
	s_nop 3
	v_pk_add_f32 v[184:185], v[38:39], v[66:67]
	s_waitcnt lgkmcnt(0)
	v_mfma_f32_16x16x32_bf16 v[68:71], v[72:75], v[2:5], v[68:71]
	ds_read_b128 v[72:75], v210 offset:2368
	ds_read_b128 v[80:83], v210 offset:4608
	ds_read_b128 v[84:87], v210 offset:4672
	ds_read_b128 v[88:91], v210 offset:6912
	ds_read_b128 v[92:95], v210 offset:6976
	s_waitcnt lgkmcnt(0)
	v_mfma_f32_16x16x32_bf16 v[20:23], v[20:23], v[6:9], v[188:191]
	v_add_f32_e64 v186, v36, v64
	v_add_f32_e64 v187, v37, v65
	s_waitcnt vmcnt(3)
	v_pk_add_f32 v[180:181], v[26:27], v[70:71]
	v_pk_add_f32 v[182:183], v[24:25], v[68:69]
	v_mfma_f32_16x16x32_bf16 v[76:79], v[76:79], v[6:9], 0
	v_add_f32_e64 v188, v34, v62
	v_add_f32_e64 v189, v35, v63
	v_pk_add_f32 v[190:191], v[32:33], v[60:61]
	s_waitcnt lgkmcnt(3)
	v_mfma_f32_16x16x32_bf16 v[10:13], v[80:83], v[6:9], 0
	s_waitcnt lgkmcnt(1)
; __device__ __forceinline__ void attn_phase(LAS unsigned char* lds, const bf16_t* QKV, const float* TBL  , bf16_t* O, int tid, int wave, int lane, int G) {
;     ...
;             for (int t = 0; t < 2; ++t) s[i + 4][t] = s[i + 4][t] + tb2[i][t];
;         __builtin_amdgcn_sched_barrier(0);
; #pragma unroll
;         for (int i = 0; i < 8; ++i) { const bf16_t* src = vsrc + (size_t)i * 64 * 64;
; #pragma unroll
;             for (int j = 0; j < 4; ++j) vr[i >> 1][i & 1][j] = *(const u32x4*)(src + (size_t)j * 8 * 64); }
;         __builtin_amdgcn_sched_barrier(0);
;         float mx = -1e30f;
; #pragma unroll
;         for (int i = 0; i < 8; ++i)
; #pragma unroll
;             for (int t = 0; t < 2; ++t) mx = fmaxf(fmaxf(mx, fmaxf(s[i][t][0], s[i][t][1])), fmaxf(s[i][t][2], s[i][t][3]));
;         mx = fmaxf(mx, __shfl_xor(mx, 16)); mx = fmaxf(mx, __shfl_xor(mx, 32));
	v_mfma_f32_16x16x32_bf16 v[6:9], v[88:91], v[6:9], 0
	v_mfma_f32_16x16x32_bf16 v[72:75], v[72:75], v[2:5], v[76:79]
	v_mfma_f32_16x16x32_bf16 v[10:13], v[84:87], v[2:5], v[10:13]
	s_waitcnt lgkmcnt(0)
	v_mfma_f32_16x16x32_bf16 v[6:9], v[92:95], v[2:5], v[6:9]
	s_waitcnt vmcnt(2)
	s_nop 3
	v_pk_add_f32 v[176:177], v[30:31], v[74:75]
	v_pk_add_f32 v[178:179], v[28:29], v[72:73]
	s_waitcnt vmcnt(1)
	v_pk_add_f32 v[172:173], v[46:47], v[12:13]
	v_pk_add_f32 v[174:175], v[44:45], v[10:11]
	v_mfma_f32_16x16x32_bf16 v[158:161], v[40:43], v[2:5], v[20:23]
	s_waitcnt vmcnt(0)
	v_pk_add_f32 v[168:169], v[50:51], v[8:9]
	v_pk_add_f32 v[170:171], v[48:49], v[6:7]
	v_lshl_add_u64 v[2:3], v[18:19], 0, s[10:11]
	v_add_co_u32_e32 v4, vcc, s73, v18
	s_mov_b32 s10, 0x10002000
	s_nop 0
	v_addc_co_u32_e32 v5, vcc, 0, v19, vcc
	global_load_dwordx4 v[98:101], v[2:3], off offset:1024
	global_load_dwordx4 v[102:105], v[2:3], off offset:2048
	global_load_dwordx4 v[110:113], v[4:5], off
	global_load_dwordx4 v[106:109], v[2:3], off offset:3072
	v_add_co_u32_e32 v2, vcc, s10, v18
	s_mov_b32 s10, 0x10004000
	s_nop 0
	v_addc_co_u32_e32 v3, vcc, 0, v19, vcc
	global_load_dwordx4 v[114:117], v[2:3], off
	global_load_dwordx4 v[118:121], v[2:3], off offset:1024
	global_load_dwordx4 v[122:125], v[2:3], off offset:2048
	global_load_dwordx4 v[126:129], v[2:3], off offset:3072
	v_add_co_u32_e32 v2, vcc, s10, v18
	s_mov_b32 s10, 0x10006000
	s_nop 0
	v_addc_co_u32_e32 v3, vcc, 0, v19, vcc
	global_load_dwordx4 v[66:69], v[2:3], off
	global_load_dwordx4 v[70:73], v[2:3], off offset:1024
	global_load_dwordx4 v[74:77], v[2:3], off offset:2048
	global_load_dwordx4 v[78:81], v[2:3], off offset:3072
	v_add_co_u32_e32 v2, vcc, s10, v18
	s_mov_b32 s10, 0x10008000
	s_nop 0
	v_addc_co_u32_e32 v3, vcc, 0, v19, vcc
	global_load_dwordx4 v[82:85], v[2:3], off
	global_load_dwordx4 v[86:89], v[2:3], off offset:1024
	global_load_dwordx4 v[90:93], v[2:3], off offset:2048
	global_load_dwordx4 v[94:97], v[2:3], off offset:3072
	v_add_co_u32_e32 v2, vcc, s10, v18
	s_mov_b32 s10, 0x1000a000
	s_nop 0
	v_addc_co_u32_e32 v3, vcc, 0, v19, vcc
	global_load_dwordx4 v[34:37], v[2:3], off
	global_load_dwordx4 v[38:41], v[2:3], off offset:1024
	global_load_dwordx4 v[42:45], v[2:3], off offset:2048
	global_load_dwordx4 v[46:49], v[2:3], off offset:3072
	v_add_co_u32_e32 v2, vcc, s10, v18
	s_mov_b32 s10, 0x1000c000
	s_nop 0
	v_addc_co_u32_e32 v3, vcc, 0, v19, vcc
	v_add_co_u32_e32 v14, vcc, s10, v18
	s_mov_b32 s10, 0x1000e000
	s_nop 0
	v_addc_co_u32_e32 v15, vcc, 0, v19, vcc
	v_add_co_u32_e32 v30, vcc, s10, v18
	global_load_dwordx4 v[50:53], v[2:3], off
	global_load_dwordx4 v[54:57], v[2:3], off offset:1024
	global_load_dwordx4 v[58:61], v[2:3], off offset:2048
	global_load_dwordx4 v[62:65], v[2:3], off offset:3072
	v_addc_co_u32_e32 v31, vcc, 0, v19, vcc
	global_load_dwordx4 v[2:5], v[14:15], off
	global_load_dwordx4 v[6:9], v[14:15], off offset:1024
	global_load_dwordx4 v[10:13], v[14:15], off offset:2048
	s_nop 0
	global_load_dwordx4 v[14:17], v[14:15], off offset:3072
	s_nop 0
	global_load_dwordx4 v[18:21], v[30:31], off
	global_load_dwordx4 v[22:25], v[30:31], off offset:1024
	global_load_dwordx4 v[26:29], v[30:31], off offset:2048
	s_nop 0
	global_load_dwordx4 v[30:33], v[30:31], off offset:3072
	v_max_f32_e32 v0, v155, v155
	v_max_f32_e32 v204, v154, v154
	v_max_f32_e32 v0, v204, v0
	v_max_f32_e32 v204, v157, v157
	v_max_f32_e32 v205, v156, v156
	v_max_f32_e32 v204, v205, v204
	s_mov_b32 s10, 0xf149f2ca
	v_max3_f32 v0, v0, s10, v204
	v_max_f32_e32 v204, v151, v151
	v_max_f32_e32 v205, v150, v150
	v_max_f32_e32 v204, v205, v204
	v_max_f32_e32 v205, v153, v153
	v_max_f32_e32 v212, v152, v152
	v_max_f32_e32 v205, v212, v205
	v_max3_f32 v0, v0, v204, v205
	v_max_f32_e32 v204, v143, v143
	v_max_f32_e32 v205, v142, v142
	v_max_f32_e32 v204, v205, v204
	v_max_f32_e32 v205, v145, v145
	v_max_f32_e32 v212, v144, v144
	v_max_f32_e32 v205, v212, v205
	v_max3_f32 v0, v0, v204, v205
	v_max_f32_e32 v204, v147, v147
	v_max_f32_e32 v205, v146, v146
	v_max_f32_e32 v204, v205, v204
	v_max_f32_e32 v205, v149, v149
	v_max_f32_e32 v212, v148, v148
	v_max_f32_e32 v205, v212, v205
	v_max3_f32 v0, v0, v204, v205
	v_max_f32_e32 v204, v139, v139
	v_max_f32_e32 v205, v138, v138
	v_max_f32_e32 v204, v205, v204
	v_max_f32_e32 v205, v141, v141
	v_max_f32_e32 v212, v140, v140
	v_max_f32_e32 v205, v212, v205
	v_max3_f32 v0, v0, v204, v205
	v_max_f32_e32 v204, v135, v135
	v_max_f32_e32 v205, v134, v134
	v_max_f32_e32 v204, v205, v204
	v_max_f32_e32 v205, v137, v137
	v_max_f32_e32 v212, v136, v136
	v_max_f32_e32 v205, v212, v205
	v_max3_f32 v0, v0, v204, v205
	v_max_f32_e32 v204, v131, v131
	v_max_f32_e32 v205, v130, v130
	v_max_f32_e32 v204, v205, v204
	v_max_f32_e32 v205, v133, v133
	v_max_f32_e32 v212, v132, v132
	v_max_f32_e32 v205, v212, v205
	v_max3_f32 v0, v0, v204, v205
	v_max_f32_e32 v204, v159, v159
	v_max_f32_e32 v205, v158, v158
	v_max_f32_e32 v204, v205, v204
	v_max_f32_e32 v205, v161, v161
	v_max_f32_e32 v212, v160, v160
	v_max_f32_e32 v205, v212, v205
	v_max3_f32 v0, v0, v204, v205
	v_max_f32_e32 v204, v198, v199
	v_max_f32_e32 v205, v196, v197
	v_max3_f32 v0, v0, v204, v205
	v_max_f32_e32 v204, v194, v195
	v_max_f32_e32 v205, v192, v193
	v_max3_f32 v0, v0, v204, v205
	v_max_f32_e32 v204, v190, v191
	v_max_f32_e32 v205, v188, v189
	v_max3_f32 v0, v0, v204, v205
	v_max_f32_e32 v204, v186, v187
	v_max_f32_e32 v205, v184, v185
	v_max3_f32 v0, v0, v204, v205
	v_max_f32_e32 v204, v182, v183
	v_max_f32_e32 v205, v180, v181
	v_max3_f32 v0, v0, v204, v205
	v_max_f32_e32 v204, v178, v179
	v_max_f32_e32 v205, v176, v177
	v_max3_f32 v0, v0, v204, v205
	v_max_f32_e32 v204, v174, v175
	v_max_f32_e32 v205, v172, v173
	v_max3_f32 v0, v0, v204, v205
	v_max_f32_e32 v204, v170, v171
	v_max_f32_e32 v205, v168, v169
	v_max3_f32 v204, v0, v204, v205
	v_and_b32_e32 v205, 64, v237
	v_xor_b32_e32 v0, 16, v237
	v_add_u32_e32 v205, 64, v205
	v_cmp_lt_i32_e32 vcc, v0, v205
	s_waitcnt vmcnt(29)
; __device__ __forceinline__ void attn_phase(LAS unsigned char* lds, const bf16_t* QKV, const float* TBL  , bf16_t* O, int tid, int wave, int lane, int G) {
;     ...
;         for (int i = 0; i < 8; ++i)
; #pragma unroll
;             for (int t = 0; t < 2; ++t) mx = fmaxf(fmaxf(mx, fmaxf(s[i][t][0], s[i][t][1])), fmaxf(s[i][t][2], s[i][t][3]));
;         mx = fmaxf(mx, __shfl_xor(mx, 16)); mx = fmaxf(mx, __shfl_xor(mx, 32));
;         float sum = 0.f;
; #pragma unroll
;         for (int i = 0; i < 8; ++i)
; #pragma unroll
;             for (int t = 0; t < 2; ++t)
; #pragma unroll
;                 for (int e = 0; e < 4; ++e) { const float pe = __builtin_amdgcn_exp2f(s[i][t][e] - mx); s[i][t][e] = pe; sum += pe; }
;         sum += __shfl_xor(sum, 16); sum += __shfl_xor(sum, 32);
;         f32x4 o[4];
; #pragma unroll
;         for (int dt = 0; dt < 4; ++dt) o[dt] = (f32x4){0.f, 0.f, 0.f, 0.f};
;         const unsigned ad = vt_addr + (unsigned)((4 * fq + (fr >> 2)) * 144 + 8 * (fr & 3));
; #pragma unroll
;         for (int ip = 0; ip < 4; ++ip) {
; #pragma unroll
;             for (int rr = 0; rr < 2; ++rr) { LAS unsigned char* dst = vt + rr * 4608 + vkey * 144 + vch * 16;
; #pragma unroll
;                 for (int j = 0; j < 4; ++j) *(LAS u32x4*)(dst + j * 8 * 144) = vr[ip][rr][j]; }
;             union { u32x4 w; bf16x8 v; } pf0, pf1; pf0.w = pack8(s[2 * ip][0], s[2 * ip][1]); pf1.w = pack8(s[2 * ip + 1][0], s[2 * ip + 1][1]);
;             s16x4 ta0, ta1, ta2, ta3, tb0, tb1, tb2, tb3, ua0, ua1, ua2, ua3, ub0, ub1, ub2, ub3;
;             asm volatile("ds_read_b64_tr_b16 %0, %16\n\tds_read_b64_tr_b16 %1, %16 offset:32\n\tds_read_b64_tr_b16 %2, %16 offset:64\n\tds_read_b64_tr_b16 %3, %16 offset:96\n\t"
;                          "ds_read_b64_tr_b16 %4, %16 offset:2304\n\tds_read_b64_tr_b16 %5, %16 offset:2336\n\tds_read_b64_tr_b16 %6, %16 offset:2368\n\tds_read_b64_tr_b16 %7, %16 offset:2400\n\t"
;                          "ds_read_b64_tr_b16 %8, %16 offset:4608\n\tds_read_b64_tr_b16 %9, %16 offset:4640\n\tds_read_b64_tr_b16 %10, %16 offset:4672\n\tds_read_b64_tr_b16 %11, %16 offset:4704\n\t"
;                          "ds_read_b64_tr_b16 %12, %16 offset:6912\n\tds_read_b64_tr_b16 %13, %16 offset:6944\n\tds_read_b64_tr_b16 %14, %16 offset:6976\n\tds_read_b64_tr_b16 %15, %16 offset:7008\n\ts_waitcnt lgkmcnt(0)"
	ds_write_b128 v209, v[110:113]
	ds_write_b128 v209, v[98:101] offset:1152
	ds_write_b128 v209, v[102:105] offset:2304
	s_waitcnt vmcnt(28)
	ds_write_b128 v209, v[106:109] offset:3456
	s_waitcnt vmcnt(27)
	ds_write_b128 v209, v[114:117] offset:4608
	s_waitcnt vmcnt(26)
	ds_write_b128 v209, v[118:121] offset:5760
	s_waitcnt vmcnt(25)
	ds_write_b128 v209, v[122:125] offset:6912
	s_waitcnt vmcnt(24)
	ds_write_b128 v209, v[126:129] offset:8064
	v_cndmask_b32_e32 v0, v237, v0, vcc
	v_lshlrev_b32_e32 v0, 2, v0
	ds_bpermute_b32 v212, v0, v204
	s_lshl_b32 s26, s17, 7
	s_add_i32 s12, s12, s38
	s_cmp_lt_i32 s12, 0x10000
	s_waitcnt lgkmcnt(0)
	v_max_f32_e32 v212, v212, v212
	v_max_f32_e32 v204, v204, v212
	v_xor_b32_e32 v212, 32, v237
	v_cmp_lt_i32_e32 vcc, v212, v205
	s_nop 1
	v_cndmask_b32_e32 v205, v237, v212, vcc
	v_lshlrev_b32_e32 v212, 2, v205
	ds_bpermute_b32 v205, v212, v204
	s_waitcnt lgkmcnt(0)
	v_max_f32_e32 v205, v205, v205
	v_max_f32_e32 v213, v204, v205
	v_sub_f32_e32 v154, v154, v213
	v_exp_f32_e32 v154, v154
	v_sub_f32_e32 v155, v155, v213
	v_exp_f32_e32 v155, v155
	v_sub_f32_e32 v156, v156, v213
	v_exp_f32_e32 v156, v156
	v_sub_f32_e32 v157, v157, v213
	v_exp_f32_e32 v157, v157
	v_sub_f32_e32 v150, v150, v213
	v_add_f32_e32 v204, 0, v154
	v_exp_f32_e32 v150, v150
	v_sub_f32_e32 v151, v151, v213
	v_add_f32_e32 v204, v155, v204
	v_exp_f32_e32 v151, v151
	v_sub_f32_e32 v152, v152, v213
	v_add_f32_e32 v204, v156, v204
	v_exp_f32_e32 v152, v152
	v_sub_f32_e32 v153, v153, v213
	v_add_f32_e32 v204, v157, v204
	v_exp_f32_e32 v153, v153
	v_sub_f32_e32 v142, v142, v213
	v_add_f32_e32 v204, v150, v204
	v_exp_f32_e32 v142, v142
	v_sub_f32_e32 v143, v143, v213
	v_add_f32_e32 v204, v151, v204
	v_exp_f32_e32 v143, v143
	v_sub_f32_e32 v144, v144, v213
	v_add_f32_e32 v204, v152, v204
	v_exp_f32_e32 v144, v144
	v_sub_f32_e32 v145, v145, v213
	v_add_f32_e32 v204, v153, v204
	v_exp_f32_e32 v145, v145
	v_sub_f32_e32 v146, v146, v213
	v_add_f32_e32 v204, v142, v204
	v_exp_f32_e32 v146, v146
	v_sub_f32_e32 v147, v147, v213
	v_add_f32_e32 v204, v143, v204
	v_exp_f32_e32 v147, v147
	v_sub_f32_e32 v148, v148, v213
	v_add_f32_e32 v204, v144, v204
	v_exp_f32_e32 v148, v148
	v_sub_f32_e32 v149, v149, v213
	v_add_f32_e32 v204, v145, v204
	v_exp_f32_e32 v149, v149
	v_sub_f32_e32 v138, v138, v213
	v_add_f32_e32 v204, v146, v204
	v_exp_f32_e32 v138, v138
	v_sub_f32_e32 v139, v139, v213
	v_add_f32_e32 v204, v147, v204
	v_exp_f32_e32 v139, v139
	v_sub_f32_e32 v140, v140, v213
	v_add_f32_e32 v204, v148, v204
	v_exp_f32_e32 v140, v140
	v_sub_f32_e32 v141, v141, v213
	v_add_f32_e32 v204, v149, v204
	v_exp_f32_e32 v141, v141
	v_sub_f32_e32 v134, v134, v213
	v_add_f32_e32 v204, v138, v204
	v_exp_f32_e32 v205, v134
	v_sub_f32_e32 v135, v135, v213
	v_add_f32_e32 v134, v139, v204
	v_exp_f32_e32 v204, v135
	v_sub_f32_e32 v135, v136, v213
	v_add_f32_e32 v134, v140, v134
	v_exp_f32_e32 v214, v135
	v_sub_f32_e32 v135, v137, v213
	v_add_f32_e32 v134, v141, v134
	v_exp_f32_e32 v215, v135
	v_sub_f32_e32 v130, v130, v213
	v_add_f32_e32 v134, v205, v134
	v_exp_f32_e32 v216, v130
	v_sub_f32_e32 v131, v131, v213
	v_add_f32_e32 v130, v204, v134
	v_exp_f32_e32 v217, v131
	v_sub_f32_e32 v131, v132, v213
	v_add_f32_e32 v130, v214, v130
	v_exp_f32_e32 v218, v131
	v_sub_f32_e32 v131, v133, v213
	v_add_f32_e32 v130, v215, v130
	v_exp_f32_e32 v219, v131
	v_sub_f32_e32 v131, v158, v213
	v_add_f32_e32 v130, v216, v130
	v_exp_f32_e32 v158, v131
	v_sub_f32_e32 v131, v159, v213
	v_add_f32_e32 v130, v217, v130
	v_exp_f32_e32 v159, v131
	v_sub_f32_e32 v131, v160, v213
	v_add_f32_e32 v130, v218, v130
	v_exp_f32_e32 v160, v131
	v_sub_f32_e32 v131, v161, v213
	v_add_f32_e32 v130, v219, v130
	v_exp_f32_e32 v161, v131
	v_sub_f32_e32 v131, v198, v213
	v_add_f32_e32 v130, v158, v130
	v_exp_f32_e32 v198, v131
	v_sub_f32_e32 v131, v199, v213
	v_add_f32_e32 v130, v159, v130
	v_exp_f32_e32 v199, v131
	v_sub_f32_e32 v131, v196, v213
	v_add_f32_e32 v130, v160, v130
	v_exp_f32_e32 v196, v131
	v_sub_f32_e32 v131, v197, v213
	v_add_f32_e32 v130, v161, v130
	v_exp_f32_e32 v197, v131
	v_sub_f32_e32 v131, v194, v213
	v_add_f32_e32 v130, v198, v130
	v_exp_f32_e32 v194, v131
	v_add_f32_e32 v130, v199, v130
	v_add_f32_e32 v130, v196, v130
	v_add_f32_e32 v130, v197, v130
	v_add_f32_e32 v220, v194, v130
	v_sub_f32_e32 v130, v195, v213
	v_exp_f32_e32 v195, v130
	v_sub_f32_e32 v130, v192, v213
	v_exp_f32_e32 v192, v130
	v_sub_f32_e32 v130, v193, v213
	v_exp_f32_e32 v193, v130
	v_cvt_pk_bf16_f32 v98, v154, v155
	v_cvt_pk_bf16_f32 v99, v156, v157
	v_cvt_pk_bf16_f32 v100, v150, v151
	v_cvt_pk_bf16_f32 v101, v152, v153
	v_cvt_pk_bf16_f32 v102, v142, v143
	v_cvt_pk_bf16_f32 v103, v144, v145
	v_cvt_pk_bf16_f32 v104, v146, v147
	v_cvt_pk_bf16_f32 v105, v148, v149
	ds_read_b64_tr_b16 v[134:135], v208
	ds_read_b64_tr_b16 v[130:131], v208 offset:32
	ds_read_b64_tr_b16 v[126:127], v208 offset:64
	ds_read_b64_tr_b16 v[122:123], v208 offset:96
	ds_read_b64_tr_b16 v[136:137], v208 offset:2304
	ds_read_b64_tr_b16 v[132:133], v208 offset:2336
	ds_read_b64_tr_b16 v[128:129], v208 offset:2368
	ds_read_b64_tr_b16 v[124:125], v208 offset:2400
	ds_read_b64_tr_b16 v[118:119], v208 offset:4608
	ds_read_b64_tr_b16 v[114:115], v208 offset:4640
	ds_read_b64_tr_b16 v[110:111], v208 offset:4672
	ds_read_b64_tr_b16 v[106:107], v208 offset:4704
	ds_read_b64_tr_b16 v[120:121], v208 offset:6912
	ds_read_b64_tr_b16 v[116:117], v208 offset:6944
	ds_read_b64_tr_b16 v[112:113], v208 offset:6976
	ds_read_b64_tr_b16 v[108:109], v208 offset:7008
	s_waitcnt lgkmcnt(0)
	v_sub_f32_e32 v143, v190, v213
	v_mfma_f32_16x16x32_bf16 v[134:137], v[134:137], v[98:101], 0
	s_waitcnt vmcnt(23)
; __device__ __forceinline__ void attn_phase(LAS unsigned char* lds, const bf16_t* QKV, const float* TBL  , bf16_t* O, int tid, int wave, int lane, int G) {
;     ...
;         for (int ip = 0; ip < 4; ++ip) {
; #pragma unroll
;             for (int rr = 0; rr < 2; ++rr) { LAS unsigned char* dst = vt + rr * 4608 + vkey * 144 + vch * 16;
; #pragma unroll
;                 for (int j = 0; j < 4; ++j) *(LAS u32x4*)(dst + j * 8 * 144) = vr[ip][rr][j]; }
;             union { u32x4 w; bf16x8 v; } pf0, pf1; pf0.w = pack8(s[2 * ip][0], s[2 * ip][1]); pf1.w = pack8(s[2 * ip + 1][0], s[2 * ip + 1][1]);
;             s16x4 ta0, ta1, ta2, ta3, tb0, tb1, tb2, tb3, ua0, ua1, ua2, ua3, ub0, ub1, ub2, ub3;
;             asm volatile("ds_read_b64_tr_b16 %0, %16\n\tds_read_b64_tr_b16 %1, %16 offset:32\n\tds_read_b64_tr_b16 %2, %16 offset:64\n\tds_read_b64_tr_b16 %3, %16 offset:96\n\t"
;                          "ds_read_b64_tr_b16 %4, %16 offset:2304\n\tds_read_b64_tr_b16 %5, %16 offset:2336\n\tds_read_b64_tr_b16 %6, %16 offset:2368\n\tds_read_b64_tr_b16 %7, %16 offset:2400\n\t"
;                          "ds_read_b64_tr_b16 %8, %16 offset:4608\n\tds_read_b64_tr_b16 %9, %16 offset:4640\n\tds_read_b64_tr_b16 %10, %16 offset:4672\n\tds_read_b64_tr_b16 %11, %16 offset:4704\n\t"
;                          "ds_read_b64_tr_b16 %12, %16 offset:6912\n\tds_read_b64_tr_b16 %13, %16 offset:6944\n\tds_read_b64_tr_b16 %14, %16 offset:6976\n\tds_read_b64_tr_b16 %15, %16 offset:7008\n\ts_waitcnt lgkmcnt(0)"
;                          : "=&v"(ta0), "=&v"(ta1), "=&v"(ta2), "=&v"(ta3), "=&v"(tb0), "=&v"(tb1), "=&v"(tb2), "=&v"(tb3), "=&v"(ua0), "=&v"(ua1), "=&v"(ua2), "=&v"(ua3), "=&v"(ub0), "=&v"(ub1), "=&v"(ub2), "=&v"(ub3) : "v"(ad) : "memory");
;             bf16x8 vf;
;             vf = (bf16x8){ta0[0], ta0[1], ta0[2], ta0[3], tb0[0], tb0[1], tb0[2], tb0[3]}; o[0] = __builtin_amdgcn_mfma_f32_16x16x32_bf16(vf, pf0.v, o[0], 0, 0, 0);
;             vf = (bf16x8){ta1[0], ta1[1], ta1[2], ta1[3], tb1[0], tb1[1], tb1[2], tb1[3]}; o[1] = __builtin_amdgcn_mfma_f32_16x16x32_bf16(vf, pf0.v, o[1], 0, 0, 0);
;             vf = (bf16x8){ta2[0], ta2[1], ta2[2], ta2[3], tb2[0], tb2[1], tb2[2], tb2[3]}; o[2] = __builtin_amdgcn_mfma_f32_16x16x32_bf16(vf, pf0.v, o[2], 0, 0, 0);
	ds_write_b128 v209, v[66:69]
	s_waitcnt vmcnt(22)
	ds_write_b128 v209, v[70:73] offset:1152
	s_waitcnt vmcnt(21)
	ds_write_b128 v209, v[74:77] offset:2304
	s_waitcnt vmcnt(20)
	ds_write_b128 v209, v[78:81] offset:3456
	s_waitcnt vmcnt(19)
	ds_write_b128 v209, v[82:85] offset:4608
	s_waitcnt vmcnt(18)
	ds_write_b128 v209, v[86:89] offset:5760
	s_waitcnt vmcnt(17)
	ds_write_b128 v209, v[90:93] offset:6912
	s_waitcnt vmcnt(16)
	ds_write_b128 v209, v[94:97] offset:8064
	v_cvt_pk_bf16_f32 v66, v138, v139
	v_cvt_pk_bf16_f32 v67, v140, v141
	v_mfma_f32_16x16x32_bf16 v[126:129], v[126:129], v[98:101], 0
	v_cvt_pk_bf16_f32 v68, v205, v204
	v_cvt_pk_bf16_f32 v69, v214, v215
	v_cvt_pk_bf16_f32 v70, v216, v217
	v_mfma_f32_16x16x32_bf16 v[130:133], v[130:133], v[98:101], 0
	v_cvt_pk_bf16_f32 v71, v218, v219
	v_cvt_pk_bf16_f32 v72, v158, v159
	v_cvt_pk_bf16_f32 v73, v160, v161
	v_mfma_f32_16x16x32_bf16 v[98:101], v[122:125], v[98:101], 0
	v_exp_f32_e32 v143, v143
	v_sub_f32_e32 v144, v191, v213
	v_add_f32_e32 v142, v195, v220
	v_mfma_f32_16x16x32_bf16 v[118:121], v[118:121], v[102:105], v[134:137]
	v_exp_f32_e32 v144, v144
	v_sub_f32_e32 v145, v188, v213
	v_add_f32_e32 v142, v192, v142
	v_mfma_f32_16x16x32_bf16 v[110:113], v[110:113], v[102:105], v[126:129]
	v_exp_f32_e32 v145, v145
	v_sub_f32_e32 v123, v189, v213
	v_add_f32_e32 v142, v193, v142
	v_mfma_f32_16x16x32_bf16 v[114:117], v[114:117], v[102:105], v[130:133]
	v_exp_f32_e32 v123, v123
	v_sub_f32_e32 v124, v186, v213
	v_add_f32_e32 v122, v143, v142
	v_mfma_f32_16x16x32_bf16 v[98:101], v[106:109], v[102:105], v[98:101]
	ds_read_b64_tr_b16 v[106:107], v208
	ds_read_b64_tr_b16 v[102:103], v208 offset:32
	ds_read_b64_tr_b16 v[94:95], v208 offset:64
	ds_read_b64_tr_b16 v[90:91], v208 offset:96
	ds_read_b64_tr_b16 v[108:109], v208 offset:2304
	ds_read_b64_tr_b16 v[104:105], v208 offset:2336
	ds_read_b64_tr_b16 v[96:97], v208 offset:2368
	ds_read_b64_tr_b16 v[92:93], v208 offset:2400
	ds_read_b64_tr_b16 v[86:87], v208 offset:4608
	ds_read_b64_tr_b16 v[82:83], v208 offset:4640
	ds_read_b64_tr_b16 v[78:79], v208 offset:4672
	ds_read_b64_tr_b16 v[74:75], v208 offset:4704
	ds_read_b64_tr_b16 v[88:89], v208 offset:6912
	ds_read_b64_tr_b16 v[84:85], v208 offset:6944
	ds_read_b64_tr_b16 v[80:81], v208 offset:6976
	ds_read_b64_tr_b16 v[76:77], v208 offset:7008
	s_waitcnt lgkmcnt(0)
	v_exp_f32_e32 v124, v124
	v_sub_f32_e32 v125, v187, v213
	v_mfma_f32_16x16x32_bf16 v[106:109], v[106:109], v[66:69], v[118:121]
	v_add_f32_e32 v122, v144, v122
	v_exp_f32_e32 v125, v125
	v_add_f32_e32 v122, v145, v122
	v_mfma_f32_16x16x32_bf16 v[94:97], v[94:97], v[66:69], v[110:113]
	v_sub_f32_e32 v118, v184, v213
	v_exp_f32_e32 v118, v118
	v_sub_f32_e32 v119, v185, v213
	v_mfma_f32_16x16x32_bf16 v[102:105], v[102:105], v[66:69], v[114:117]
	v_add_f32_e32 v122, v123, v122
	s_waitcnt vmcnt(15)
	ds_write_b128 v209, v[34:37]
	s_waitcnt vmcnt(14)
	ds_write_b128 v209, v[38:41] offset:1152
	s_waitcnt vmcnt(13)
	ds_write_b128 v209, v[42:45] offset:2304
	s_waitcnt vmcnt(12)
	ds_write_b128 v209, v[46:49] offset:3456
	s_waitcnt vmcnt(11)
	ds_write_b128 v209, v[50:53] offset:4608
	s_waitcnt vmcnt(10)
	ds_write_b128 v209, v[54:57] offset:5760
	s_waitcnt vmcnt(9)
	ds_write_b128 v209, v[58:61] offset:6912
	s_waitcnt vmcnt(8)
	ds_write_b128 v209, v[62:65] offset:8064
	v_exp_f32_e32 v114, v119
	v_mfma_f32_16x16x32_bf16 v[66:69], v[90:93], v[66:69], v[98:101]
	v_sub_f32_e32 v115, v182, v213
	v_cvt_pk_bf16_f32 v34, v198, v199
	v_cvt_pk_bf16_f32 v35, v196, v197
	v_mfma_f32_16x16x32_bf16 v[86:89], v[86:89], v[70:73], v[106:109]
	v_cvt_pk_bf16_f32 v36, v194, v195
	v_cvt_pk_bf16_f32 v37, v192, v193
	v_cvt_pk_bf16_f32 v38, v143, v144
	v_mfma_f32_16x16x32_bf16 v[78:81], v[78:81], v[70:73], v[94:97]
	v_cvt_pk_bf16_f32 v39, v145, v123
	v_cvt_pk_bf16_f32 v40, v124, v125
	v_cvt_pk_bf16_f32 v41, v118, v114
	v_mfma_f32_16x16x32_bf16 v[82:85], v[82:85], v[70:73], v[102:105]
	v_add_f32_e32 v122, v124, v122
	v_exp_f32_e32 v115, v115
	v_sub_f32_e32 v90, v183, v213
	v_mfma_f32_16x16x32_bf16 v[66:69], v[74:77], v[70:73], v[66:69]
	ds_read_b64_tr_b16 v[74:75], v208
	ds_read_b64_tr_b16 v[70:71], v208 offset:32
	ds_read_b64_tr_b16 v[62:63], v208 offset:64
	ds_read_b64_tr_b16 v[58:59], v208 offset:96
	ds_read_b64_tr_b16 v[76:77], v208 offset:2304
	ds_read_b64_tr_b16 v[72:73], v208 offset:2336
	ds_read_b64_tr_b16 v[64:65], v208 offset:2368
	ds_read_b64_tr_b16 v[60:61], v208 offset:2400
	ds_read_b64_tr_b16 v[54:55], v208 offset:4608
	ds_read_b64_tr_b16 v[50:51], v208 offset:4640
	ds_read_b64_tr_b16 v[46:47], v208 offset:4672
	ds_read_b64_tr_b16 v[42:43], v208 offset:4704
	ds_read_b64_tr_b16 v[56:57], v208 offset:6912
	ds_read_b64_tr_b16 v[52:53], v208 offset:6944
	ds_read_b64_tr_b16 v[48:49], v208 offset:6976
	ds_read_b64_tr_b16 v[44:45], v208 offset:7008
	s_waitcnt lgkmcnt(0)
; __device__ __forceinline__ void attn_phase(LAS unsigned char* lds, const bf16_t* QKV, const float* TBL  , bf16_t* O, int tid, int wave, int lane, int G) {
;     ...
;         sum += __shfl_xor(sum, 16); sum += __shfl_xor(sum, 32);
;         f32x4 o[4];
; #pragma unroll
;         for (int dt = 0; dt < 4; ++dt) o[dt] = (f32x4){0.f, 0.f, 0.f, 0.f};
;         const unsigned ad = vt_addr + (unsigned)((4 * fq + (fr >> 2)) * 144 + 8 * (fr & 3));
; #pragma unroll
;         for (int ip = 0; ip < 4; ++ip) {
; #pragma unroll
;             for (int rr = 0; rr < 2; ++rr) { LAS unsigned char* dst = vt + rr * 4608 + vkey * 144 + vch * 16;
; #pragma unroll
;                 for (int j = 0; j < 4; ++j) *(LAS u32x4*)(dst + j * 8 * 144) = vr[ip][rr][j]; }
;             union { u32x4 w; bf16x8 v; } pf0, pf1; pf0.w = pack8(s[2 * ip][0], s[2 * ip][1]); pf1.w = pack8(s[2 * ip + 1][0], s[2 * ip + 1][1]);
;             s16x4 ta0, ta1, ta2, ta3, tb0, tb1, tb2, tb3, ua0, ua1, ua2, ua3, ub0, ub1, ub2, ub3;
;             asm volatile("ds_read_b64_tr_b16 %0, %16\n\tds_read_b64_tr_b16 %1, %16 offset:32\n\tds_read_b64_tr_b16 %2, %16 offset:64\n\tds_read_b64_tr_b16 %3, %16 offset:96\n\t"
;                          "ds_read_b64_tr_b16 %4, %16 offset:2304\n\tds_read_b64_tr_b16 %5, %16 offset:2336\n\tds_read_b64_tr_b16 %6, %16 offset:2368\n\tds_read_b64_tr_b16 %7, %16 offset:2400\n\t"
;                          "ds_read_b64_tr_b16 %8, %16 offset:4608\n\tds_read_b64_tr_b16 %9, %16 offset:4640\n\tds_read_b64_tr_b16 %10, %16 offset:4672\n\tds_read_b64_tr_b16 %11, %16 offset:4704\n\t"
;                          "ds_read_b64_tr_b16 %12, %16 offset:6912\n\tds_read_b64_tr_b16 %13, %16 offset:6944\n\tds_read_b64_tr_b16 %14, %16 offset:6976\n\tds_read_b64_tr_b16 %15, %16 offset:7008\n\ts_waitcnt lgkmcnt(0)"
;                          : "=&v"(ta0), "=&v"(ta1), "=&v"(ta2), "=&v"(ta3), "=&v"(tb0), "=&v"(tb1), "=&v"(tb2), "=&v"(tb3), "=&v"(ua0), "=&v"(ua1), "=&v"(ua2), "=&v"(ua3), "=&v"(ub0), "=&v"(ub1), "=&v"(ub2), "=&v"(ub3) : "v"(ad) : "memory");
;             bf16x8 vf;
;             vf = (bf16x8){ta0[0], ta0[1], ta0[2], ta0[3], tb0[0], tb0[1], tb0[2], tb0[3]}; o[0] = __builtin_amdgcn_mfma_f32_16x16x32_bf16(vf, pf0.v, o[0], 0, 0, 0);
;             vf = (bf16x8){ta1[0], ta1[1], ta1[2], ta1[3], tb1[0], tb1[1], tb1[2], tb1[3]}; o[1] = __builtin_amdgcn_mfma_f32_16x16x32_bf16(vf, pf0.v, o[1], 0, 0, 0);
	v_add_f32_e32 v122, v125, v122
	v_exp_f32_e32 v90, v90
	v_mfma_f32_16x16x32_bf16 v[74:77], v[74:77], v[34:37], v[86:89]
	v_sub_f32_e32 v91, v180, v213
	v_add_f32_e32 v110, v118, v122
	v_exp_f32_e32 v91, v91
	v_sub_f32_e32 v92, v181, v213
	v_mfma_f32_16x16x32_bf16 v[62:65], v[62:65], v[34:37], v[78:81]
	v_add_f32_e32 v110, v114, v110
	v_exp_f32_e32 v92, v92
	v_sub_f32_e32 v94, v178, v213
	v_mfma_f32_16x16x32_bf16 v[70:73], v[70:73], v[34:37], v[82:85]
	v_add_f32_e32 v110, v115, v110
	v_exp_f32_e32 v94, v94
	v_sub_f32_e32 v95, v179, v213
	v_mfma_f32_16x16x32_bf16 v[34:37], v[58:61], v[34:37], v[66:69]
	v_add_f32_e32 v93, v90, v110
	v_exp_f32_e32 v86, v95
	v_sub_f32_e32 v87, v176, v213
	v_mfma_f32_16x16x32_bf16 v[54:57], v[54:57], v[38:41], v[74:77]
	v_add_f32_e32 v93, v91, v93
	v_exp_f32_e32 v87, v87
	v_sub_f32_e32 v82, v177, v213
	v_sub_f32_e32 v83, v174, v213
	v_sub_f32_e32 v79, v175, v213
	v_sub_f32_e32 v58, v172, v213
	v_sub_f32_e32 v59, v173, v213
	v_sub_f32_e32 v60, v170, v213
	v_sub_f32_e32 v61, v171, v213
	v_sub_f32_e32 v66, v168, v213
	v_mfma_f32_16x16x32_bf16 v[46:49], v[46:49], v[38:41], v[62:65]
	v_add_f32_e32 v93, v92, v93
	v_exp_f32_e32 v82, v82
	v_exp_f32_e32 v78, v83
	v_sub_f32_e32 v63, v169, v213
	v_exp_f32_e32 v79, v79
	v_exp_f32_e32 v58, v58
	v_exp_f32_e32 v59, v59
	v_exp_f32_e32 v60, v60
	v_mfma_f32_16x16x32_bf16 v[50:53], v[50:53], v[38:41], v[70:73]
	v_exp_f32_e32 v61, v61
	v_exp_f32_e32 v62, v66
	v_exp_f32_e32 v63, v63
	v_mfma_f32_16x16x32_bf16 v[34:37], v[42:45], v[38:41], v[34:37]
	s_waitcnt vmcnt(7)
	ds_write_b128 v209, v[2:5]
	s_waitcnt vmcnt(6)
	ds_write_b128 v209, v[6:9] offset:1152
	s_waitcnt vmcnt(5)
	ds_write_b128 v209, v[10:13] offset:2304
	s_waitcnt vmcnt(4)
	ds_write_b128 v209, v[14:17] offset:3456
	s_waitcnt vmcnt(3)
	ds_write_b128 v209, v[18:21] offset:4608
	s_waitcnt vmcnt(2)
	ds_write_b128 v209, v[22:25] offset:5760
	s_waitcnt vmcnt(1)
	ds_write_b128 v209, v[26:29] offset:6912
	s_waitcnt vmcnt(0)
	ds_write_b128 v209, v[30:33] offset:8064
	v_cvt_pk_bf16_f32 v2, v115, v90
	v_cvt_pk_bf16_f32 v3, v91, v92
	v_cvt_pk_bf16_f32 v4, v94, v86
	v_cvt_pk_bf16_f32 v5, v87, v82
	v_cvt_pk_bf16_f32 v6, v78, v79
	v_cvt_pk_bf16_f32 v7, v58, v59
	v_cvt_pk_bf16_f32 v8, v60, v61
	v_cvt_pk_bf16_f32 v9, v62, v63
	ds_read_b64_tr_b16 v[42:43], v208
	ds_read_b64_tr_b16 v[38:39], v208 offset:32
	ds_read_b64_tr_b16 v[30:31], v208 offset:64
	ds_read_b64_tr_b16 v[26:27], v208 offset:96
	ds_read_b64_tr_b16 v[44:45], v208 offset:2304
	ds_read_b64_tr_b16 v[40:41], v208 offset:2336
	ds_read_b64_tr_b16 v[32:33], v208 offset:2368
	ds_read_b64_tr_b16 v[28:29], v208 offset:2400
	ds_read_b64_tr_b16 v[22:23], v208 offset:4608
	ds_read_b64_tr_b16 v[18:19], v208 offset:4640
	ds_read_b64_tr_b16 v[14:15], v208 offset:4672
	ds_read_b64_tr_b16 v[10:11], v208 offset:4704
	ds_read_b64_tr_b16 v[24:25], v208 offset:6912
	ds_read_b64_tr_b16 v[20:21], v208 offset:6944
	ds_read_b64_tr_b16 v[16:17], v208 offset:6976
	ds_read_b64_tr_b16 v[12:13], v208 offset:7008
	s_waitcnt lgkmcnt(0)
	s_nop 0
	v_mfma_f32_16x16x32_bf16 v[42:45], v[42:45], v[2:5], v[54:57]
	s_nop 2
	v_add_f32_e32 v54, v94, v93
	v_add_f32_e32 v54, v86, v54
	v_add_f32_e32 v54, v87, v54
	v_mfma_f32_16x16x32_bf16 v[38:41], v[38:41], v[2:5], v[50:53]
	s_nop 2
	v_add_f32_e32 v50, v82, v54
	v_add_f32_e32 v50, v78, v50
	v_add_f32_e32 v50, v79, v50
	v_mfma_f32_16x16x32_bf16 v[30:33], v[30:33], v[2:5], v[46:49]
	s_nop 2
	v_add_f32_e32 v46, v58, v50
	v_add_f32_e32 v46, v59, v46
	v_add_f32_e32 v46, v60, v46
	v_mfma_f32_16x16x32_bf16 v[2:5], v[26:29], v[2:5], v[34:37]
	v_add_f32_e32 v26, v61, v46
	v_add_f32_e32 v26, v62, v26
	v_add_f32_e32 v26, v63, v26
	ds_bpermute_b32 v0, v0, v26
	v_mfma_f32_16x16x32_bf16 v[22:25], v[22:25], v[6:9], v[42:45]
	s_waitcnt lgkmcnt(0)
	v_add_f32_e32 v0, v26, v0
	ds_bpermute_b32 v26, v212, v0
	v_mfma_f32_16x16x32_bf16 v[18:21], v[18:21], v[6:9], v[38:41]
	s_waitcnt lgkmcnt(0)
	v_add_f32_e32 v0, v0, v26
	v_div_scale_f32 v26, s[10:11], v0, v0, 1.0
	v_rcp_f32_e32 v27, v26
	v_mfma_f32_16x16x32_bf16 v[14:17], v[14:17], v[6:9], v[30:33]
	v_mfma_f32_16x16x32_bf16 v[2:5], v[10:13], v[6:9], v[2:5]
	v_fma_f32 v6, -v26, v27, 1.0
	v_fmac_f32_e32 v27, v6, v27
	v_div_scale_f32 v6, vcc, 1.0, v0, 1.0
	v_mul_f32_e32 v7, v6, v27
	v_fma_f32 v8, -v26, v7, v6
	v_fmac_f32_e32 v7, v8, v27
	v_fma_f32 v6, -v26, v7, v6
	v_div_fmas_f32 v6, v6, v27, v7
	v_div_fixup_f32 v0, v6, v0, 1.0
	v_mul_f32_e32 v6, v0, v22
	v_mul_f32_e32 v7, v0, v23
	v_cvt_pk_bf16_f32 v6, v6, v7
	v_mul_f32_e32 v7, v0, v24
	v_mul_f32_e32 v8, v0, v25
	v_cvt_pk_bf16_f32 v7, v7, v8
	ds_write_b64 v211, v[6:7]
	v_mul_f32_e32 v6, v0, v18
	v_mul_f32_e32 v7, v0, v19
	v_cvt_pk_bf16_f32 v6, v6, v7
	v_mul_f32_e32 v7, v0, v20
	v_mul_f32_e32 v8, v0, v21
	v_cvt_pk_bf16_f32 v7, v7, v8
	ds_write_b64 v211, v[6:7] offset:32
	v_mul_f32_e32 v6, v0, v14
	v_mul_f32_e32 v7, v0, v15
	v_cvt_pk_bf16_f32 v6, v6, v7
	v_mul_f32_e32 v7, v0, v16
	v_mul_f32_e32 v2, v0, v2
	v_mul_f32_e32 v3, v0, v3
	v_mul_f32_e32 v8, v0, v17
	v_cvt_pk_bf16_f32 v7, v7, v8
	ds_write_b64 v211, v[6:7] offset:64
	v_cvt_pk_bf16_f32 v2, v2, v3
	v_mul_f32_e32 v3, v0, v4
	v_mul_f32_e32 v0, v0, v5
	v_cvt_pk_bf16_f32 v3, v3, v0
	ds_write_b64 v211, v[2:3] offset:96
	v_mov_b32_e32 v11, s9
	v_or_b32_e32 v10, s8, v164
	ds_read_b128 v[2:5], v209
	ds_read_b128 v[6:9], v209 offset:1152
	v_lshlrev_b64 v[10:11], 11, v[10:11]
	v_lshl_add_u64 v[10:11], s[44:45], 0, v[10:11]
	v_lshl_add_u64 v[10:11], v[10:11], 0, s[26:27]
	v_lshl_add_u64 v[10:11], v[10:11], 0, v[166:167]
	s_waitcnt lgkmcnt(1)
	global_store_dwordx4 v[10:11], v[2:5], off
	s_nop 1
	v_add_co_u32_e32 v2, vcc, 0x4000, v10
	s_nop 1
	v_addc_co_u32_e32 v3, vcc, 0, v11, vcc
	s_waitcnt lgkmcnt(0)
	global_store_dwordx4 v[2:3], v[6:9], off
	s_waitcnt lgkmcnt(0)
	s_cbranch_scc0 .LBB0_372
